# attention unit epilogue: O^T halves exchanged with v_permlane32_swap so each lane stores 16 B (8 dwordx4 stores per unit instead of 16 dwordx2)
# speedup vs baseline: 1.0123x; 1.0053x over previous
; DI int tid_opq() { int t = threadIdx.x; asm volatile("" : "+v"(t)); return t; }
; DI unsigned pk2(float lo, float hi) { const f32x2_t v = {lo, hi}; return __builtin_bit_cast(unsigned, __builtin_convertvector(v, bf16x2_t)); }
; DI void attn_unit(LAS unsigned char* lds, const bf16_t* Q, const bf16_t* Kn, const bf16_t* Kpe, const bf16_t* Vt, bf16_t* O, int b, int h, int qb) {
;     ...
;     const int tid2 = tid_opq(), lane2 = tid2 & 63, hi2 = lane2 >> 5;
;     const int qrow2 = b * 4096 + qb * 512 + __builtin_amdgcn_readfirstlane(tid2 >> 6) * 64 + (lane2 & 31);
; #pragma unroll
;     for (int j = 0; j < 2; ++j) {
;         const float l = lsum[j] + __shfl_xor(lsum[j], 32), inv = 1.0f / l;
;         bf16_t* op = O + (size_t)(qrow2 + 32 * j) * 1024 + h * 64;
; #pragma unroll
;         for (int g4 = 0; g4 < 4; ++g4) {
;             u32x2 w0, w1;
;             w0.x = pk2(o[j][0][4 * g4] * inv, o[j][0][4 * g4 + 1] * inv); w0.y = pk2(o[j][0][4 * g4 + 2] * inv, o[j][0][4 * g4 + 3] * inv);
;             w1.x = pk2(o[j][1][4 * g4] * inv, o[j][1][4 * g4 + 1] * inv); w1.y = pk2(o[j][1][4 * g4 + 2] * inv, o[j][1][4 * g4 + 3] * inv);
;             *(u32x2*)(op + 8 * g4 + 4 * hi2) = w0; *(u32x2*)(op + 32 + 8 * g4 + 4 * hi2) = w1;
;         }
;     }
.LBB0_1104:
	ds_bpermute_b32 v65, v240, v213
	v_mov_b32_e32 v67, v232
	s_waitcnt lgkmcnt(0)
	v_add_f32_e32 v65, v213, v65
	v_div_scale_f32 v66, s[6:7], v65, v65, 1.0
	v_rcp_f32_e32 v68, v66
	v_readfirstlane_b32 s2, v67
	s_andn2_b32 s2, s2, 63
	s_add_i32 s2, s2, s9
	v_fma_f32 v69, -v66, v68, 1.0
	v_fmac_f32_e32 v68, v69, v68
	v_div_scale_f32 v69, vcc, 1.0, v65, 1.0
	v_mul_f32_e32 v70, v69, v68
	v_fma_f32 v71, -v66, v70, v69
	v_fmac_f32_e32 v70, v71, v68
	v_fma_f32 v66, -v66, v70, v69
	v_and_or_b32 v64, v67, 31, s2
	s_lshl_b32 s2, s8, 7
	v_div_fmas_f32 v66, v66, v68, v70
	s_add_u32 s6, s79, s2
	v_div_fixup_f32 v66, v66, v65, 1.0
	v_ashrrev_i32_e32 v65, 31, v64
	s_addc_u32 s7, s86, 0
	v_lshlrev_b64 v[68:69], 11, v[64:65]
	v_lshrrev_b32_e32 v65, 1, v67
	v_lshl_add_u64 v[68:69], s[6:7], 0, v[68:69]
	v_and_b32_e32 v188, 16, v65
	v_lshl_add_u64 v[68:69], v[68:69], 0, v[188:189]
	v_pk_mul_f32 v[48:49], v[48:49], v[66:67] op_sel_hi:[1,0]
	v_pk_mul_f32 v[50:51], v[50:51], v[66:67] op_sel_hi:[1,0]
	v_pk_mul_f32 v[52:53], v[52:53], v[66:67] op_sel_hi:[1,0]
	v_pk_mul_f32 v[54:55], v[54:55], v[66:67] op_sel_hi:[1,0]
	v_cvt_pk_bf16_f32 v72, v48, v49
	v_cvt_pk_bf16_f32 v73, v50, v51
	v_cvt_pk_bf16_f32 v74, v52, v53
	v_cvt_pk_bf16_f32 v75, v54, v55
	s_nop 1
	v_permlane32_swap_b32_e32 v72, v74
	v_permlane32_swap_b32_e32 v73, v75
	global_store_dwordx4 v[68:69], v[72:75], off
	v_pk_mul_f32 v[56:57], v[56:57], v[66:67] op_sel_hi:[1,0]
	v_pk_mul_f32 v[58:59], v[58:59], v[66:67] op_sel_hi:[1,0]
	v_pk_mul_f32 v[60:61], v[60:61], v[66:67] op_sel_hi:[1,0]
	v_pk_mul_f32 v[62:63], v[62:63], v[66:67] op_sel_hi:[1,0]
	v_cvt_pk_bf16_f32 v76, v56, v57
	v_cvt_pk_bf16_f32 v77, v58, v59
	v_cvt_pk_bf16_f32 v78, v60, v61
	v_cvt_pk_bf16_f32 v79, v62, v63
	s_nop 1
	v_permlane32_swap_b32_e32 v76, v78
	v_permlane32_swap_b32_e32 v77, v79
	global_store_dwordx4 v[68:69], v[76:79], off offset:32
	v_pk_mul_f32 v[16:17], v[16:17], v[66:67] op_sel_hi:[1,0]
	v_pk_mul_f32 v[18:19], v[18:19], v[66:67] op_sel_hi:[1,0]
	v_pk_mul_f32 v[20:21], v[20:21], v[66:67] op_sel_hi:[1,0]
	v_pk_mul_f32 v[22:23], v[22:23], v[66:67] op_sel_hi:[1,0]
	v_cvt_pk_bf16_f32 v72, v16, v17
	v_cvt_pk_bf16_f32 v73, v18, v19
	v_cvt_pk_bf16_f32 v74, v20, v21
	v_cvt_pk_bf16_f32 v75, v22, v23
	s_nop 1
	v_permlane32_swap_b32_e32 v72, v74
	v_permlane32_swap_b32_e32 v73, v75
	global_store_dwordx4 v[68:69], v[72:75], off offset:64
	v_pk_mul_f32 v[24:25], v[24:25], v[66:67] op_sel_hi:[1,0]
	v_pk_mul_f32 v[26:27], v[26:27], v[66:67] op_sel_hi:[1,0]
	v_pk_mul_f32 v[28:29], v[28:29], v[66:67] op_sel_hi:[1,0]
	v_pk_mul_f32 v[30:31], v[30:31], v[66:67] op_sel_hi:[1,0]
	v_cvt_pk_bf16_f32 v76, v24, v25
	v_cvt_pk_bf16_f32 v77, v26, v27
	v_cvt_pk_bf16_f32 v78, v28, v29
	v_cvt_pk_bf16_f32 v79, v30, v31
	s_nop 1
	v_permlane32_swap_b32_e32 v76, v78
	v_permlane32_swap_b32_e32 v77, v79
	global_store_dwordx4 v[68:69], v[76:79], off offset:96
	ds_bpermute_b32 v80, v240, v212
	s_waitcnt lgkmcnt(0)
	v_add_f32_e32 v80, v212, v80
	v_div_scale_f32 v81, s[8:9], v80, v80, 1.0
	v_rcp_f32_e32 v84, v81
	s_nop 0
	v_fma_f32 v82, -v81, v84, 1.0
	v_fmac_f32_e32 v84, v82, v84
	v_div_scale_f32 v82, vcc, 1.0, v80, 1.0
	v_mul_f32_e32 v83, v82, v84
	v_fma_f32 v85, -v81, v83, v82
	v_fmac_f32_e32 v83, v85, v84
	v_fma_f32 v82, -v81, v83, v82
	v_or_b32_e32 v86, 32, v64
	v_div_fmas_f32 v82, v82, v84, v83
	v_ashrrev_i32_e32 v87, 31, v86
	v_div_fixup_f32 v82, v82, v80, 1.0
	v_lshlrev_b64 v[86:87], 11, v[86:87]
	v_lshl_add_u64 v[86:87], s[6:7], 0, v[86:87]
	v_lshl_add_u64 v[86:87], v[86:87], 0, v[188:189]
	v_pk_mul_f32 v[32:33], v[32:33], v[82:83] op_sel_hi:[1,0]
	v_pk_mul_f32 v[34:35], v[34:35], v[82:83] op_sel_hi:[1,0]
	v_pk_mul_f32 v[36:37], v[36:37], v[82:83] op_sel_hi:[1,0]
	v_pk_mul_f32 v[38:39], v[38:39], v[82:83] op_sel_hi:[1,0]
	v_cvt_pk_bf16_f32 v72, v32, v33
	v_cvt_pk_bf16_f32 v73, v34, v35
	v_cvt_pk_bf16_f32 v74, v36, v37
	v_cvt_pk_bf16_f32 v75, v38, v39
	s_nop 1
	v_permlane32_swap_b32_e32 v72, v74
	v_permlane32_swap_b32_e32 v73, v75
	global_store_dwordx4 v[86:87], v[72:75], off
	v_pk_mul_f32 v[40:41], v[40:41], v[82:83] op_sel_hi:[1,0]
	v_pk_mul_f32 v[42:43], v[42:43], v[82:83] op_sel_hi:[1,0]
	v_pk_mul_f32 v[44:45], v[44:45], v[82:83] op_sel_hi:[1,0]
	v_pk_mul_f32 v[46:47], v[46:47], v[82:83] op_sel_hi:[1,0]
	v_cvt_pk_bf16_f32 v76, v40, v41
	v_cvt_pk_bf16_f32 v77, v42, v43
	v_cvt_pk_bf16_f32 v78, v44, v45
	v_cvt_pk_bf16_f32 v79, v46, v47
	s_nop 1
	v_permlane32_swap_b32_e32 v76, v78
	v_permlane32_swap_b32_e32 v77, v79
	global_store_dwordx4 v[86:87], v[76:79], off offset:32
	v_pk_mul_f32 v[0:1], v[0:1], v[82:83] op_sel_hi:[1,0]
	v_pk_mul_f32 v[2:3], v[2:3], v[82:83] op_sel_hi:[1,0]
	v_pk_mul_f32 v[4:5], v[4:5], v[82:83] op_sel_hi:[1,0]
	v_pk_mul_f32 v[6:7], v[6:7], v[82:83] op_sel_hi:[1,0]
	v_cvt_pk_bf16_f32 v72, v0, v1
	v_cvt_pk_bf16_f32 v73, v2, v3
	v_cvt_pk_bf16_f32 v74, v4, v5
	v_cvt_pk_bf16_f32 v75, v6, v7
	s_nop 1
	v_permlane32_swap_b32_e32 v72, v74
	v_permlane32_swap_b32_e32 v73, v75
	global_store_dwordx4 v[86:87], v[72:75], off offset:64
	v_pk_mul_f32 v[8:9], v[8:9], v[82:83] op_sel_hi:[1,0]
	v_pk_mul_f32 v[10:11], v[10:11], v[82:83] op_sel_hi:[1,0]
	v_pk_mul_f32 v[12:13], v[12:13], v[82:83] op_sel_hi:[1,0]
	v_pk_mul_f32 v[14:15], v[14:15], v[82:83] op_sel_hi:[1,0]
	v_cvt_pk_bf16_f32 v76, v8, v9
	v_cvt_pk_bf16_f32 v77, v10, v11
	v_cvt_pk_bf16_f32 v78, v12, v13
	v_cvt_pk_bf16_f32 v79, v14, v15
	s_nop 1
	v_permlane32_swap_b32_e32 v76, v78
	v_permlane32_swap_b32_e32 v77, v79
	global_store_dwordx4 v[86:87], v[76:79], off offset:96
	s_add_i32 s35, s35, 1
	s_mov_b64 s[6:7], 0
